# attention loop: K-fragment ds_reads prefetched one pair ahead (v248-255), K/V staging ds_writes moved from step tail into PV MFMA gaps
# speedup vs baseline: 1.0393x; 1.0393x over previous
; #define SBAR() __builtin_amdgcn_sched_barrier(0)
; __device__ __forceinline__ unsigned cvtpk(float lo, float hi) { unsigned r; asm volatile("v_cvt_pk_bf16_f32 %0, %1, %2" : "=v"(r) : "v"(lo), "v"(hi)); return r; }
; #define SLOAD(k0) do { sr_.vs0 = *(const bf16x8*)(&Vh[(long)((k0) + sr) * LDK + sc]); sr_.vs1 = *(const bf16x8*)(&Vh[(long)((k0) + 32 + sr) * LDK + sc]); \
;     sr_.ks0 = *(const bf16x8*)(&Kh[(long)((k0) + sr) * LDK + sc]); sr_.ks1 = *(const bf16x8*)(&Kh[(long)((k0) + 32 + sr) * LDK + sc]); } while (0)
; __device__ __forceinline__ void qkt_fin(f32x16& n0, f32x16& n1, const bf16_t* Ks, const bf16x8* qr, const f32x16& negm, int r32, int hi, ...
;   float psa = 0.f, psb = 0.f; u32x4 wa, wb, wc, wd;
;     ...
; #pragma unroll
;   for (int d0 = 0; d0 < 8; ++d0) { int cb = (d0 * 16 + hi * 8) * 2;
;     bf16x8 b0 = *reinterpret_cast<const bf16x8*>((const char*)Ks + KSWZ(r32, cb));
;     bf16x8 b1 = *reinterpret_cast<const bf16x8*>((const char*)Ks + KSWZ(32 + r32, cb));
;     SBAR(); if (d0 == 0) n0 = __builtin_amdgcn_mfma_f32_32x32x16_bf16(b0, qr[0], negm, 0, 0, 0); else n0 = __builtin_amdgcn_mfma_f32_32x32x16_bf16(b0, qr[d0], n0, 0, 0, 0);
;     SBAR(); QF_CHUNK(2 * d0); SBAR();
;     if (d0 == 0) n1 = __builtin_amdgcn_mfma_f32_32x32x16_bf16(b1, qr[0], negm, 0, 0, 0); else n1 = __builtin_amdgcn_mfma_f32_32x32x16_bf16(b1, qr[d0], n1, 0, 0, 0);
;     SBAR(); QF_CHUNK(2 * d0 + 1); SBAR();
;     if (d0 == 7) { vf8_read<0>(vf0, vbv); SBAR(); } }
;     ...
;   psb += P1[15]; wd[3] = cvtpk(P1[14], P1[15]);
;   l_reg = l_reg * alpha + (psa + psb);
;   pa0 = *reinterpret_cast<bf16x8*>(&wa); pa1 = *reinterpret_cast<bf16x8*>(&wb); pa2 = *reinterpret_cast<bf16x8*>(&wc); pa3 = *reinterpret_cast<bf16x8*>(&wd);
; }
; __device__ __forceinline__ void attn_item(const bf16_t* __restrict__ Qb, const bf16_t* __restrict__ Kh, const bf16_t* __restrict__ Vh, const bf16_t* __restrict__ Zb, ...
;     ...
;     SBAR(); SLOAD((j + 1) * KVBLK); SBAR();
;     qkt_fin(pB0, pB1, (const bf16_t*)(lds + s_cur + KOFF), qr, negm, r32, hi, pA0, pA1, alA, l_reg, pa0, pa1, pa2, pa3, vfa, vb0 + s_prev); SBAR();
.LBB0_453:
	s_mov_b32 s79, s77
	s_mov_b32 s77, s8
	v_add_co_u32_e32 v98, vcc, s67, v214
	s_nop 1
	v_addc_co_u32_e32 v99, vcc, -1, v215, vcc
	v_add_co_u32_e32 v100, vcc, s68, v214
	s_nop 1
	v_addc_co_u32_e32 v101, vcc, -1, v215, vcc
	global_load_dwordx4 v[180:183], v[98:99], off
	global_load_dwordx4 v[184:187], v[98:99], off offset:-512
	global_load_dwordx4 v[192:195], v[100:101], off
	global_load_dwordx4 v[188:191], v[100:101], off offset:-512
	s_add_i32 s8, s79, 0
	v_add_u32_e32 v196, s8, v236
	ds_read_b128 v[98:101], v196 offset:16384
	ds_read_b128 v[196:199], v196 offset:24576
	v_add_u32_e32 v252, s8, v237
	ds_read_b128 v[248:251], v252 offset:16384
	ds_read_b128 v[252:255], v252 offset:24576
	v_add_u32_e32 v0, s77, v235
	s_waitcnt lgkmcnt(3)
	v_mfma_f32_32x32x16_bf16 v[132:147], v[98:101], v[152:155], v[66:81]
	v_exp_f32_e32 v82, v82
	s_waitcnt lgkmcnt(2)
	v_mfma_f32_32x32x16_bf16 v[98:113], v[196:199], v[152:155], v[66:81]
	v_exp_f32_e32 v83, v83
	v_add_f32_e32 v245, v115, v114
	v_cvt_pk_bf16_f32 v196, v114, v115
	v_add_u32_e32 v206, s8, v238
	ds_read_b128 v[202:205], v206 offset:16384
	ds_read_b128 v[206:209], v206 offset:24576
	s_waitcnt lgkmcnt(3)
	v_mfma_f32_32x32x16_bf16 v[132:147], v[248:251], v[160:163], v[132:147]
	v_exp_f32_e32 v84, v84
	v_add_f32_e32 v245, v116, v245
	v_add_f32_e32 v246, v82, v83
	s_waitcnt lgkmcnt(2)
	v_mfma_f32_32x32x16_bf16 v[98:113], v[252:255], v[160:163], v[98:113]
	v_exp_f32_e32 v85, v85
	v_add_f32_e32 v245, v117, v245
	v_add_f32_e32 v246, v246, v84
	v_cvt_pk_bf16_f32 v197, v116, v117
	v_cvt_pk_bf16_f32 v200, v82, v83
	v_add_u32_e32 v252, s8, v239
	ds_read_b128 v[248:251], v252 offset:16384
	ds_read_b128 v[252:255], v252 offset:24576
	s_waitcnt lgkmcnt(3)
	v_mfma_f32_32x32x16_bf16 v[132:147], v[202:205], v[148:151], v[132:147]
	v_exp_f32_e32 v86, v86
	v_add_f32_e32 v245, v118, v245
	v_add_f32_e32 v246, v246, v85
	s_waitcnt lgkmcnt(2)
	v_mfma_f32_32x32x16_bf16 v[98:113], v[206:209], v[148:151], v[98:113]
	v_exp_f32_e32 v87, v87
	v_add_f32_e32 v245, v119, v245
	v_add_f32_e32 v246, v246, v86
	v_cvt_pk_bf16_f32 v198, v118, v119
	v_cvt_pk_bf16_f32 v201, v84, v85
	v_add_u32_e32 v208, s8, v240
	ds_read_b128 v[204:207], v208 offset:16384
	ds_read_b128 v[208:211], v208 offset:24576
	s_waitcnt lgkmcnt(3)
	v_mfma_f32_32x32x16_bf16 v[132:147], v[248:251], v[156:159], v[132:147]
	v_exp_f32_e32 v88, v88
	v_add_f32_e32 v245, v120, v245
	v_add_f32_e32 v246, v246, v87
	s_waitcnt lgkmcnt(2)
	v_mfma_f32_32x32x16_bf16 v[98:113], v[252:255], v[156:159], v[98:113]
	v_exp_f32_e32 v89, v89
	v_add_f32_e32 v245, v121, v245
	v_add_f32_e32 v246, v246, v88
	v_cvt_pk_bf16_f32 v199, v120, v121
	v_cvt_pk_bf16_f32 v202, v86, v87
	v_add_u32_e32 v252, s8, v241
	ds_read_b128 v[248:251], v252 offset:16384
	ds_read_b128 v[252:255], v252 offset:24576
	s_waitcnt lgkmcnt(3)
	v_mfma_f32_32x32x16_bf16 v[132:147], v[204:207], v[168:171], v[132:147]
	v_exp_f32_e32 v90, v90
	v_add_f32_e32 v245, v122, v245
	v_add_f32_e32 v246, v246, v89
	s_waitcnt lgkmcnt(2)
	v_mfma_f32_32x32x16_bf16 v[98:113], v[208:211], v[168:171], v[98:113]
	v_exp_f32_e32 v91, v91
	v_add_f32_e32 v245, v123, v245
	v_add_f32_e32 v246, v246, v90
	v_cvt_pk_bf16_f32 v204, v122, v123
	v_cvt_pk_bf16_f32 v203, v88, v89
	v_add_u32_e32 v118, s8, v242
	ds_read_b128 v[114:117], v118 offset:16384
	ds_read_b128 v[118:121], v118 offset:24576
	s_waitcnt lgkmcnt(3)
	v_mfma_f32_32x32x16_bf16 v[132:147], v[248:251], v[176:179], v[132:147]
	v_exp_f32_e32 v92, v92
	v_add_f32_e32 v245, v124, v245
	v_add_f32_e32 v246, v246, v91
	s_waitcnt lgkmcnt(2)
	v_mfma_f32_32x32x16_bf16 v[98:113], v[252:255], v[176:179], v[98:113]
	v_exp_f32_e32 v93, v93
	v_add_f32_e32 v245, v125, v245
	v_add_f32_e32 v246, v246, v92
	v_cvt_pk_bf16_f32 v205, v124, v125
	v_cvt_pk_bf16_f32 v208, v90, v91
	v_add_u32_e32 v252, s8, v243
	ds_read_b128 v[248:251], v252 offset:16384
	ds_read_b128 v[252:255], v252 offset:24576
	s_waitcnt lgkmcnt(3)
	v_mfma_f32_32x32x16_bf16 v[132:147], v[114:117], v[164:167], v[132:147]
	v_exp_f32_e32 v94, v94
	v_add_f32_e32 v245, v126, v245
	v_add_f32_e32 v246, v246, v93
	s_waitcnt lgkmcnt(2)
	v_mfma_f32_32x32x16_bf16 v[98:113], v[118:121], v[164:167], v[98:113]
	v_exp_f32_e32 v95, v95
	v_add_f32_e32 v245, v127, v245
	v_add_f32_e32 v246, v246, v94
	v_cvt_pk_bf16_f32 v206, v126, v127
	v_cvt_pk_bf16_f32 v209, v92, v93
	s_waitcnt lgkmcnt(1)
	v_mfma_f32_32x32x16_bf16 v[132:147], v[248:251], v[172:175], v[132:147]
	v_exp_f32_e32 v96, v96
	v_add_f32_e32 v245, v128, v245
	v_add_f32_e32 v246, v246, v95
	s_waitcnt lgkmcnt(0)
	v_mfma_f32_32x32x16_bf16 v[98:113], v[252:255], v[172:175], v[98:113]
	v_exp_f32_e32 v97, v97
	v_add_f32_e32 v245, v129, v245
	v_add_f32_e32 v246, v246, v96
	v_cvt_pk_bf16_f32 v207, v128, v129
	v_cvt_pk_bf16_f32 v210, v94, v95
	v_mov_b32_e32 v131, v97
	v_cvt_pk_bf16_f32 v211, v96, v97
	ds_read_b64_tr_b16 v[94:95], v0 offset:0
	ds_read_b64_tr_b16 v[96:97], v0 offset:2048
	ds_read_b64_tr_b16 v[90:91], v0 offset:4096
	ds_read_b64_tr_b16 v[92:93], v0 offset:6144
	ds_read_b64_tr_b16 v[86:87], v0 offset:8192
	ds_read_b64_tr_b16 v[88:89], v0 offset:10240
	ds_read_b64_tr_b16 v[82:83], v0 offset:12288
	ds_read_b64_tr_b16 v[84:85], v0 offset:14336
	v_cndmask_b32_e64 v114, 0, 1, s[0:1]
	v_cmp_ne_u32_e64 s[8:9], 1, v114
	s_andn2_b64 vcc, exec, s[0:1]
	s_cbranch_vccnz .LBB0_456
; template <bool FIRST, bool DOEXP = true>
; __device__ __forceinline__ void partialSM(f32x16& p0, f32x16& p1, float& m_reg, f32x16& negm, float& alpha, const bool track = true) {
;     ...
;   float pmax = p0[0];
; #pragma unroll
;   for (int r = 1; r < 16; ++r) pmax = fmaxf(pmax, p0[r]);
; #pragma unroll
;   for (int r = 0; r < 16; ++r) pmax = fmaxf(pmax, p1[r]);
;   { auto rr = __builtin_amdgcn_permlane32_swap(__float_as_uint(pmax), __float_as_uint(pmax), false, false);
;     pmax = fmaxf(__uint_as_float(rr[0]), __uint_as_float(rr[1])); }
;   if (!FIRST && __builtin_expect(__all(pmax <= THRL), 1)) { alpha = 1.f; }
;   else { const float dl = FIRST ? pmax : fmaxf(pmax, 0.f); m_reg += dl; alpha = FIRST ? 1.f : __builtin_amdgcn_exp2f(-dl);
; #pragma unroll
;     for (int r = 0; r < 16; ++r) { p0[r] -= dl; p1[r] -= dl; }
; #pragma unroll
;     for (int r = 0; r < 16; ++r) negm[r] = -m_reg;
;     asm volatile("" : "+v"(negm)); }
	v_max_f32_e32 v114, v133, v133
	v_max_f32_e32 v115, v132, v132
	v_max_f32_e32 v114, v115, v114
	v_max3_f32 v114, v114, v134, v135
	v_max3_f32 v114, v114, v136, v137
	v_max3_f32 v114, v114, v138, v139
	v_max3_f32 v114, v114, v140, v141
	v_max3_f32 v114, v114, v142, v143
	v_max3_f32 v114, v114, v144, v145
	v_max3_f32 v114, v114, v146, v147
	v_max3_f32 v114, v114, v98, v99
	v_max3_f32 v114, v114, v100, v101
	v_max3_f32 v114, v114, v102, v103
	v_max3_f32 v114, v114, v104, v105
	v_max3_f32 v114, v114, v106, v107
	v_max3_f32 v114, v114, v108, v109
	v_max3_f32 v114, v114, v110, v111
	v_max3_f32 v114, v114, v112, v113
	v_mov_b32_e32 v115, v114
	s_nop 1
	v_permlane32_swap_b32_e32 v114, v115
	v_max_f32_e32 v115, v115, v115
	v_max_f32_e32 v114, v114, v114
	v_max_f32_e32 v114, v114, v115
	v_cmp_ge_f32_e32 vcc, s69, v114
	s_cmp_eq_u64 vcc, exec
	v_mov_b32_e32 v130, 1.0
	s_cbranch_scc1 .LBB0_457
	v_max_f32_e32 v66, v114, v114
	v_max_f32_e32 v66, 0, v66
	v_exp_f32_e64 v130, -v66
	v_add_f32_e32 v222, v222, v66
	v_sub_f32_e32 v147, v147, v66
	v_sub_f32_e32 v146, v146, v66
	v_sub_f32_e32 v145, v145, v66
	v_sub_f32_e32 v144, v144, v66
	v_sub_f32_e32 v143, v143, v66
	v_sub_f32_e32 v142, v142, v66
	v_sub_f32_e32 v141, v141, v66
	v_sub_f32_e32 v140, v140, v66
	v_sub_f32_e32 v139, v139, v66
	v_sub_f32_e32 v138, v138, v66
	v_sub_f32_e32 v137, v137, v66
	v_sub_f32_e32 v136, v136, v66
	v_sub_f32_e32 v135, v135, v66
	v_sub_f32_e32 v134, v134, v66
	v_sub_f32_e32 v133, v133, v66
	v_sub_f32_e32 v132, v132, v66
	v_sub_f32_e32 v113, v113, v66
	v_sub_f32_e32 v112, v112, v66
	v_sub_f32_e32 v111, v111, v66
	v_sub_f32_e32 v110, v110, v66
	v_sub_f32_e32 v109, v109, v66
	v_sub_f32_e32 v108, v108, v66
	v_sub_f32_e32 v107, v107, v66
	v_sub_f32_e32 v106, v106, v66
	v_sub_f32_e32 v105, v105, v66
	v_sub_f32_e32 v104, v104, v66
	v_sub_f32_e32 v103, v103, v66
	v_sub_f32_e32 v102, v102, v66
	v_sub_f32_e32 v101, v101, v66
	v_sub_f32_e32 v100, v100, v66
	v_sub_f32_e32 v99, v99, v66
	v_sub_f32_e32 v98, v98, v66
	v_xor_b32_e32 v66, 0x80000000, v222
	v_mov_b32_e32 v67, v66
	v_mov_b32_e32 v68, v66
	v_mov_b32_e32 v69, v66
	v_mov_b32_e32 v70, v66
	v_mov_b32_e32 v71, v66
	v_mov_b32_e32 v72, v66
	v_mov_b32_e32 v73, v66
	v_mov_b32_e32 v74, v66
	v_mov_b32_e32 v75, v66
	v_mov_b32_e32 v76, v66
	v_mov_b32_e32 v77, v66
	v_mov_b32_e32 v78, v66
	v_mov_b32_e32 v79, v66
	v_mov_b32_e32 v80, v66
	v_mov_b32_e32 v81, v66
	s_branch .LBB0_457

; #define SBAR() __builtin_amdgcn_sched_barrier(0)
; #define PVE_M(OD, PA, L, H, IDX) do { OD = __builtin_amdgcn_mfma_f32_32x32x16_bf16(PA, PKV(L, H), OD, 0, 0, 0); SBAR(); p[IDX] = __builtin_amdgcn_exp2f(p[IDX]); asm volatile("" : "+v"(p)); SBAR(); } while (0)
; #define SWRITE(so) do { *(bf16x8*)(lds + (so) + vst0) = sr_.vs0; *(bf16x8*)(lds + (so) + vst1) = sr_.vs1;          \
;     *(bf16x8*)(lds + (so) + kst0) = sr_.ks0; *(bf16x8*)(lds + (so) + kst1) = sr_.ks1; } while (0)
; #define SWAIT() asm volatile("s_waitcnt vmcnt(0)" ::: "memory")
; #define RESC(a) do { if (__any((a) < 1.f)) { if (hi == 0) al_l[r32] = (a); asm volatile("s_waitcnt lgkmcnt(0)" ::: "memory"); \
;     _Pragma("unroll") for (int d = 0; d < 4; ++d) _Pragma("unroll") for (int r = 0; r < 16; ++r) o[d][r] *= al_l[crow(r, hi)]; } } while (0)
; #define ROT() do { const int t_ = s_prev; s_prev = s_cur; s_cur = s_next; s_next = t_; } while (0)
; __device__ __forceinline__ void pv_exp(f32x16* o, int vb, bf16x8 pa0, bf16x8 pa1, bf16x8 pa2, bf16x8 pa3, f32x16& p, VF8& fa) {
;   VF8 fb;
;   asm volatile("s_waitcnt lgkmcnt(0)" ::: "memory"); SBAR();
;   PVE_M(o[0], pa0, fa.l0, fa.h0, 0); PVE_M(o[0], pa1, fa.l1, fa.h1, 1); vf8_read<1>(fb, vb); SBAR(); PVE_M(o[0], pa2, fa.l2, fa.h2, 2); PVE_M(o[0], pa3, fa.l3, fa.h3, 3);
;   asm volatile("s_waitcnt lgkmcnt(0)" ::: "memory"); SBAR();
;   PVE_M(o[1], pa0, fb.l0, fb.h0, 4); PVE_M(o[1], pa1, fb.l1, fb.h1, 5); vf8_read<2>(fa, vb); SBAR(); PVE_M(o[1], pa2, fb.l2, fb.h2, 6); PVE_M(o[1], pa3, fb.l3, fb.h3, 7);
;   asm volatile("s_waitcnt lgkmcnt(0)" ::: "memory"); SBAR();
;   PVE_M(o[2], pa0, fa.l0, fa.h0, 8); PVE_M(o[2], pa1, fa.l1, fa.h1, 9); vf8_read<3>(fb, vb); SBAR(); PVE_M(o[2], pa2, fa.l2, fa.h2, 10); PVE_M(o[2], pa3, fa.l3, fa.h3, 11);
;   asm volatile("s_waitcnt lgkmcnt(0)" ::: "memory"); SBAR();
;   PVE_M(o[3], pa0, fb.l0, fb.h0, 12); PVE_M(o[3], pa1, fb.l1, fb.h1, 13); PVE_M(o[3], pa2, fb.l2, fb.h2, 14); PVE_M(o[3], pa3, fb.l3, fb.h3, 15);
; }
; __device__ __forceinline__ void attn_item(const bf16_t* __restrict__ Qb, const bf16_t* __restrict__ Kh, const bf16_t* __restrict__ Vh, const bf16_t* __restrict__ Zb, ...
;     ...
;     SWAIT(); SWRITE(s_next);
;     RESC(alB); __syncthreads(); ROT();
.LBB0_457:
	s_add_i32 s80, s76, 0
	s_waitcnt lgkmcnt(0)
	v_mfma_f32_32x32x16_bf16 v[50:65], v[196:199], v[94:97], v[50:65]
	v_exp_f32_e32 v132, v132
	v_mfma_f32_32x32x16_bf16 v[50:65], v[204:207], v[90:93], v[50:65]
	v_exp_f32_e32 v133, v133
	ds_read_b64_tr_b16 v[90:91], v0 offset:0x200
	ds_read_b64_tr_b16 v[92:93], v0 offset:0xa00
	ds_read_b64_tr_b16 v[94:95], v0 offset:0x1200
	ds_read_b64_tr_b16 v[96:97], v0 offset:0x1a00
	ds_read_b64_tr_b16 v[114:115], v0 offset:0x2200
	ds_read_b64_tr_b16 v[116:117], v0 offset:0x2a00
	ds_read_b64_tr_b16 v[118:119], v0 offset:0x3200
	ds_read_b64_tr_b16 v[120:121], v0 offset:0x3a00
	s_waitcnt vmcnt(3)
	v_add_u32_e32 v248, s80, v228
	ds_write_b128 v248, v[180:183]
	v_mfma_f32_32x32x16_bf16 v[50:65], v[200:203], v[86:89], v[50:65]
	v_exp_f32_e32 v134, v134
	v_mfma_f32_32x32x16_bf16 v[50:65], v[208:211], v[82:85], v[50:65]
	v_exp_f32_e32 v135, v135
	s_waitcnt lgkmcnt(1)
	v_mfma_f32_32x32x16_bf16 v[34:49], v[196:199], v[90:93], v[34:49]
	v_exp_f32_e32 v136, v136
	v_mfma_f32_32x32x16_bf16 v[34:49], v[204:207], v[94:97], v[34:49]
	v_exp_f32_e32 v137, v137
	ds_read_b64_tr_b16 v[82:83], v0 offset:0x400
	ds_read_b64_tr_b16 v[84:85], v0 offset:0xc00
	ds_read_b64_tr_b16 v[86:87], v0 offset:0x1400
	ds_read_b64_tr_b16 v[88:89], v0 offset:0x1c00
	ds_read_b64_tr_b16 v[90:91], v0 offset:0x2400
	ds_read_b64_tr_b16 v[92:93], v0 offset:0x2c00
	ds_read_b64_tr_b16 v[94:95], v0 offset:0x3400
	ds_read_b64_tr_b16 v[96:97], v0 offset:0x3c00
	s_waitcnt vmcnt(2)
	v_add_u32_e32 v249, s80, v231
	ds_write_b128 v249, v[184:187] offset:16384
	v_mfma_f32_32x32x16_bf16 v[34:49], v[200:203], v[114:117], v[34:49]
	v_exp_f32_e32 v138, v138
	v_mfma_f32_32x32x16_bf16 v[34:49], v[208:211], v[118:121], v[34:49]
	v_exp_f32_e32 v139, v139
	s_waitcnt lgkmcnt(1)
	v_mfma_f32_32x32x16_bf16 v[18:33], v[196:199], v[82:85], v[18:33]
	v_exp_f32_e32 v140, v140
	v_mfma_f32_32x32x16_bf16 v[18:33], v[204:207], v[86:89], v[18:33]
	v_exp_f32_e32 v141, v141
	ds_read_b64_tr_b16 v[82:83], v0 offset:0x600
	ds_read_b64_tr_b16 v[84:85], v0 offset:0xe00
	ds_read_b64_tr_b16 v[86:87], v0 offset:0x1600
	ds_read_b64_tr_b16 v[88:89], v0 offset:0x1e00
	ds_read_b64_tr_b16 v[114:115], v0 offset:0x2600
	ds_read_b64_tr_b16 v[116:117], v0 offset:0x2e00
	ds_read_b64_tr_b16 v[118:119], v0 offset:0x3600
	ds_read_b64_tr_b16 v[120:121], v0 offset:0x3e00
	s_waitcnt vmcnt(1)
	v_add_u32_e32 v250, s80, v229
	ds_write_b128 v250, v[192:195]
	v_mfma_f32_32x32x16_bf16 v[18:33], v[200:203], v[90:93], v[18:33]
	v_exp_f32_e32 v142, v142
	v_mfma_f32_32x32x16_bf16 v[18:33], v[208:211], v[94:97], v[18:33]
	v_exp_f32_e32 v143, v143
	s_waitcnt lgkmcnt(1)
	v_mfma_f32_32x32x16_bf16 v[2:17], v[196:199], v[82:85], v[2:17]
	v_exp_f32_e32 v144, v144
	s_waitcnt vmcnt(0)
	v_add_u32_e32 v251, s80, v232
	ds_write_b128 v251, v[188:191] offset:16384
	v_mfma_f32_32x32x16_bf16 v[2:17], v[204:207], v[86:89], v[2:17]
	v_exp_f32_e32 v145, v145
	v_mfma_f32_32x32x16_bf16 v[2:17], v[200:203], v[114:117], v[2:17]
	v_exp_f32_e32 v146, v146
	v_mfma_f32_32x32x16_bf16 v[2:17], v[208:211], v[118:121], v[2:17]
	v_exp_f32_e32 v147, v147
	v_cmp_gt_f32_e32 vcc, 1.0, v130
	s_cbranch_vccz .LBB0_461
	s_and_saveexec_b64 s[36:37], s[6:7]
	ds_write_b32 v220, v130 offset:128
	s_or_b64 exec, exec, s[36:37]
	s_waitcnt lgkmcnt(0)
	v_add_u32_e32 v94, v213, v212
	ds_read_b128 v[82:85], v94 offset:224
	ds_read_b128 v[86:89], v94 offset:192
	ds_read_b128 v[90:93], v94 offset:160
	ds_read_b128 v[94:97], v94 offset:128
	s_waitcnt lgkmcnt(3)
	v_pk_mul_f32 v[62:63], v[62:63], v[82:83]
	s_waitcnt lgkmcnt(2)
	v_pk_mul_f32 v[58:59], v[58:59], v[86:87]
	s_waitcnt lgkmcnt(1)
	v_pk_mul_f32 v[54:55], v[54:55], v[90:91]
	v_pk_mul_f32 v[64:65], v[64:65], v[84:85]
	v_pk_mul_f32 v[60:61], v[60:61], v[88:89]
	v_pk_mul_f32 v[56:57], v[56:57], v[92:93]
	s_waitcnt lgkmcnt(0)
	v_pk_mul_f32 v[52:53], v[52:53], v[96:97]
	v_pk_mul_f32 v[50:51], v[50:51], v[94:95]
	v_pk_mul_f32 v[46:47], v[46:47], v[82:83]
	v_pk_mul_f32 v[42:43], v[42:43], v[86:87]
	v_pk_mul_f32 v[38:39], v[38:39], v[90:91]
	v_pk_mul_f32 v[48:49], v[48:49], v[84:85]
	v_pk_mul_f32 v[44:45], v[44:45], v[88:89]
	v_pk_mul_f32 v[40:41], v[40:41], v[92:93]
	v_pk_mul_f32 v[36:37], v[36:37], v[96:97]
	v_pk_mul_f32 v[34:35], v[34:35], v[94:95]
	v_pk_mul_f32 v[30:31], v[30:31], v[82:83]
	v_pk_mul_f32 v[26:27], v[26:27], v[86:87]
	v_pk_mul_f32 v[22:23], v[22:23], v[90:91]
	v_pk_mul_f32 v[32:33], v[32:33], v[84:85]
	v_pk_mul_f32 v[28:29], v[28:29], v[88:89]
	v_pk_mul_f32 v[24:25], v[24:25], v[92:93]
	v_pk_mul_f32 v[20:21], v[20:21], v[96:97]
	v_pk_mul_f32 v[18:19], v[18:19], v[94:95]
	v_pk_mul_f32 v[14:15], v[14:15], v[82:83]
	v_pk_mul_f32 v[10:11], v[10:11], v[86:87]
	v_pk_mul_f32 v[6:7], v[6:7], v[90:91]
	v_pk_mul_f32 v[16:17], v[16:17], v[84:85]
	v_pk_mul_f32 v[12:13], v[12:13], v[88:89]
	v_pk_mul_f32 v[8:9], v[8:9], v[92:93]
	v_pk_mul_f32 v[4:5], v[4:5], v[96:97]
	v_pk_mul_f32 v[2:3], v[2:3], v[94:95]
; #define SBAR() __builtin_amdgcn_sched_barrier(0)
; __device__ __forceinline__ unsigned cvtpk(float lo, float hi) { unsigned r; asm volatile("v_cvt_pk_bf16_f32 %0, %1, %2" : "=v"(r) : "v"(lo), "v"(hi)); return r; }
; #define SLOAD(k0) do { sr_.vs0 = *(const bf16x8*)(&Vh[(long)((k0) + sr) * LDK + sc]); sr_.vs1 = *(const bf16x8*)(&Vh[(long)((k0) + 32 + sr) * LDK + sc]); \
;     sr_.ks0 = *(const bf16x8*)(&Kh[(long)((k0) + sr) * LDK + sc]); sr_.ks1 = *(const bf16x8*)(&Kh[(long)((k0) + 32 + sr) * LDK + sc]); } while (0)
; __device__ __forceinline__ void qkt_fin(f32x16& n0, f32x16& n1, const bf16_t* Ks, const bf16x8* qr, const f32x16& negm, int r32, int hi, ...
;   float psa = 0.f, psb = 0.f; u32x4 wa, wb, wc, wd;
;     ...
; #pragma unroll
;   for (int d0 = 0; d0 < 8; ++d0) { int cb = (d0 * 16 + hi * 8) * 2;
;     bf16x8 b0 = *reinterpret_cast<const bf16x8*>((const char*)Ks + KSWZ(r32, cb));
;     bf16x8 b1 = *reinterpret_cast<const bf16x8*>((const char*)Ks + KSWZ(32 + r32, cb));
;     SBAR(); if (d0 == 0) n0 = __builtin_amdgcn_mfma_f32_32x32x16_bf16(b0, qr[0], negm, 0, 0, 0); else n0 = __builtin_amdgcn_mfma_f32_32x32x16_bf16(b0, qr[d0], n0, 0, 0, 0);
;     SBAR(); QF_CHUNK(2 * d0); SBAR();
;     if (d0 == 0) n1 = __builtin_amdgcn_mfma_f32_32x32x16_bf16(b1, qr[0], negm, 0, 0, 0); else n1 = __builtin_amdgcn_mfma_f32_32x32x16_bf16(b1, qr[d0], n1, 0, 0, 0);
;     SBAR(); QF_CHUNK(2 * d0 + 1); SBAR();
;     if (d0 == 7) { vf8_read<0>(vf0, vbv); SBAR(); } }
;     ...
;   psb += P1[15]; wd[3] = cvtpk(P1[14], P1[15]);
;   l_reg = l_reg * alpha + (psa + psb);
;   pa0 = *reinterpret_cast<bf16x8*>(&wa); pa1 = *reinterpret_cast<bf16x8*>(&wb); pa2 = *reinterpret_cast<bf16x8*>(&wc); pa3 = *reinterpret_cast<bf16x8*>(&wd);
; }
; __device__ __forceinline__ void attn_item(const bf16_t* __restrict__ Qb, const bf16_t* __restrict__ Kh, const bf16_t* __restrict__ Vh, const bf16_t* __restrict__ Zb, ...
;     ...
;     SBAR(); SLOAD((j + 2) * KVBLK); SBAR();
;     qkt_fin(pA0, pA1, (const bf16_t*)(lds + s_cur + KOFF), qr, negm, r32, hi, pB0, pB1, alB, l_reg, pa0, pa1, pa2, pa3, vfa, vb0 + s_prev); SBAR();
.LBB0_461:
	s_waitcnt lgkmcnt(0)
	s_barrier
	v_add_co_u32_e32 v82, vcc, 0xfffbf000, v214
	s_nop 1
	v_addc_co_u32_e32 v83, vcc, -1, v215, vcc
	global_load_dwordx4 v[188:191], v[82:83], off
	global_load_dwordx4 v[180:183], v[82:83], off offset:-512
	global_load_dwordx4 v[192:195], v[214:215], off
	global_load_dwordx4 v[184:187], v[214:215], off offset:-512
	v_add_u32_e32 v208, s80, v236
	ds_read_b128 v[204:207], v208 offset:16384
	ds_read_b128 v[208:211], v208 offset:24576
	v_add_u32_e32 v252, s80, v237
	ds_read_b128 v[248:251], v252 offset:16384
	ds_read_b128 v[252:255], v252 offset:24576
	v_add_u32_e32 v203, s79, v235
	s_waitcnt lgkmcnt(3)
	v_mfma_f32_32x32x16_bf16 v[114:129], v[204:207], v[152:155], v[66:81]
	v_exp_f32_e32 v98, v98
	s_waitcnt lgkmcnt(2)
	v_mfma_f32_32x32x16_bf16 v[82:97], v[208:211], v[152:155], v[66:81]
	v_exp_f32_e32 v99, v99
	v_add_f32_e32 v201, v133, v132
	v_cvt_pk_bf16_f32 v132, v132, v133
	v_add_u32_e32 v208, s80, v238
	ds_read_b128 v[204:207], v208 offset:16384
	ds_read_b128 v[208:211], v208 offset:24576
	s_waitcnt lgkmcnt(3)
	v_mfma_f32_32x32x16_bf16 v[114:129], v[248:251], v[160:163], v[114:129]
	v_exp_f32_e32 v100, v100
	v_add_f32_e32 v201, v134, v201
	v_add_f32_e32 v202, v98, v99
	s_waitcnt lgkmcnt(2)
	v_mfma_f32_32x32x16_bf16 v[82:97], v[252:255], v[160:163], v[82:97]
	v_exp_f32_e32 v101, v101
	v_add_f32_e32 v201, v135, v201
	v_add_f32_e32 v202, v202, v100
	v_cvt_pk_bf16_f32 v133, v134, v135
	v_cvt_pk_bf16_f32 v196, v98, v99
	v_add_u32_e32 v252, s80, v239
	ds_read_b128 v[248:251], v252 offset:16384
	ds_read_b128 v[252:255], v252 offset:24576
	s_waitcnt lgkmcnt(3)
	v_mfma_f32_32x32x16_bf16 v[114:129], v[204:207], v[148:151], v[114:129]
	v_exp_f32_e32 v102, v102
	v_add_f32_e32 v201, v136, v201
	v_add_f32_e32 v202, v202, v101
	s_waitcnt lgkmcnt(2)
	v_mfma_f32_32x32x16_bf16 v[82:97], v[208:211], v[148:151], v[82:97]
	v_exp_f32_e32 v103, v103
	v_add_f32_e32 v201, v137, v201
	v_add_f32_e32 v202, v202, v102
	v_cvt_pk_bf16_f32 v134, v136, v137
	v_cvt_pk_bf16_f32 v197, v100, v101
	v_add_u32_e32 v208, s80, v240
	ds_read_b128 v[204:207], v208 offset:16384
	ds_read_b128 v[208:211], v208 offset:24576
	s_waitcnt lgkmcnt(3)
	v_mfma_f32_32x32x16_bf16 v[114:129], v[248:251], v[156:159], v[114:129]
	v_exp_f32_e32 v104, v104
	v_add_f32_e32 v201, v138, v201
	v_add_f32_e32 v202, v202, v103
	s_waitcnt lgkmcnt(2)
	v_mfma_f32_32x32x16_bf16 v[82:97], v[252:255], v[156:159], v[82:97]
	v_exp_f32_e32 v105, v105
	v_add_f32_e32 v201, v139, v201
	v_add_f32_e32 v202, v202, v104
	v_cvt_pk_bf16_f32 v135, v138, v139
	v_cvt_pk_bf16_f32 v198, v102, v103
	v_add_u32_e32 v252, s80, v241
	ds_read_b128 v[248:251], v252 offset:16384
	ds_read_b128 v[252:255], v252 offset:24576
	s_waitcnt lgkmcnt(3)
	v_mfma_f32_32x32x16_bf16 v[114:129], v[204:207], v[168:171], v[114:129]
	v_exp_f32_e32 v106, v106
	v_add_f32_e32 v201, v140, v201
	v_add_f32_e32 v202, v202, v105
	s_waitcnt lgkmcnt(2)
	v_mfma_f32_32x32x16_bf16 v[82:97], v[208:211], v[168:171], v[82:97]
	v_exp_f32_e32 v107, v107
	v_add_f32_e32 v201, v141, v201
	v_add_f32_e32 v202, v202, v106
	v_cvt_pk_bf16_f32 v136, v140, v141
	v_cvt_pk_bf16_f32 v199, v104, v105
	v_add_u32_e32 v208, s80, v242
	ds_read_b128 v[204:207], v208 offset:16384
	ds_read_b128 v[208:211], v208 offset:24576
	s_waitcnt lgkmcnt(3)
	v_mfma_f32_32x32x16_bf16 v[114:129], v[248:251], v[176:179], v[114:129]
	v_exp_f32_e32 v108, v108
	v_add_f32_e32 v201, v142, v201
	v_add_f32_e32 v202, v202, v107
	s_waitcnt lgkmcnt(2)
	v_mfma_f32_32x32x16_bf16 v[82:97], v[252:255], v[176:179], v[82:97]
	v_exp_f32_e32 v109, v109
	v_add_f32_e32 v201, v143, v201
	v_add_f32_e32 v202, v202, v108
	v_cvt_pk_bf16_f32 v137, v142, v143
	v_cvt_pk_bf16_f32 v140, v106, v107
	v_add_u32_e32 v252, s80, v243
	ds_read_b128 v[248:251], v252 offset:16384
	ds_read_b128 v[252:255], v252 offset:24576
	s_waitcnt lgkmcnt(3)
	v_mfma_f32_32x32x16_bf16 v[114:129], v[204:207], v[164:167], v[114:129]
	v_exp_f32_e32 v110, v110
	v_add_f32_e32 v201, v144, v201
	v_add_f32_e32 v202, v202, v109
	s_waitcnt lgkmcnt(2)
	v_mfma_f32_32x32x16_bf16 v[82:97], v[208:211], v[164:167], v[82:97]
	v_exp_f32_e32 v111, v111
	v_add_f32_e32 v201, v145, v201
	v_add_f32_e32 v202, v202, v110
	v_cvt_pk_bf16_f32 v138, v144, v145
	v_cvt_pk_bf16_f32 v141, v108, v109
	s_waitcnt lgkmcnt(1)
	v_mfma_f32_32x32x16_bf16 v[114:129], v[248:251], v[172:175], v[114:129]
	v_exp_f32_e32 v112, v112
	v_add_f32_e32 v201, v146, v201
	v_add_f32_e32 v202, v202, v111
	s_waitcnt lgkmcnt(0)
	v_mfma_f32_32x32x16_bf16 v[82:97], v[252:255], v[172:175], v[82:97]
	v_exp_f32_e32 v113, v113
	v_add_f32_e32 v201, v147, v201
	v_add_f32_e32 v202, v202, v112
	v_cvt_pk_bf16_f32 v139, v146, v147
	v_cvt_pk_bf16_f32 v142, v110, v111
	ds_read_b64_tr_b16 v[144:145], v203 offset:0
	ds_read_b64_tr_b16 v[146:147], v203 offset:2048
	s_nop 0
	ds_read_b64_tr_b16 v[106:107], v203 offset:4096
	ds_read_b64_tr_b16 v[108:109], v203 offset:6144
	ds_read_b64_tr_b16 v[102:103], v203 offset:8192
	ds_read_b64_tr_b16 v[104:105], v203 offset:10240
	ds_read_b64_tr_b16 v[98:99], v203 offset:12288
	ds_read_b64_tr_b16 v[100:101], v203 offset:14336
	v_cvt_pk_bf16_f32 v143, v112, v113
	s_and_b64 vcc, exec, s[8:9]
	v_mov_b32_e32 v200, 1.0
	s_cbranch_vccnz .LBB0_463
	v_max_f32_e32 v110, v115, v115
	v_max_f32_e32 v111, v114, v114
	v_max_f32_e32 v110, v111, v110
	v_max3_f32 v110, v110, v116, v117
	v_max3_f32 v110, v110, v118, v119
	v_max3_f32 v110, v110, v120, v121
	v_max3_f32 v110, v110, v122, v123
	v_max3_f32 v110, v110, v124, v125
	v_max3_f32 v110, v110, v126, v127
	v_max3_f32 v110, v110, v128, v129
	v_max3_f32 v110, v110, v82, v83
	v_max3_f32 v110, v110, v84, v85
	v_max3_f32 v110, v110, v86, v87
	v_max3_f32 v110, v110, v88, v89
	v_max3_f32 v110, v110, v90, v91
	v_max3_f32 v110, v110, v92, v93
	v_max3_f32 v110, v110, v94, v95
	v_max3_f32 v110, v110, v96, v97
	v_mov_b32_e32 v111, v110
	s_nop 1
	v_permlane32_swap_b32_e32 v110, v111
	v_max_f32_e32 v111, v111, v111
	v_max_f32_e32 v110, v110, v110
	v_max_f32_e32 v110, v110, v111
	v_cmp_ge_f32_e32 vcc, s69, v110
	s_cmp_eq_u64 vcc, exec
	v_mov_b32_e32 v200, 1.0
	s_cbranch_scc0 .LBB0_469
; #define SBAR() __builtin_amdgcn_sched_barrier(0)
; #define PVE_M(OD, PA, L, H, IDX) do { OD = __builtin_amdgcn_mfma_f32_32x32x16_bf16(PA, PKV(L, H), OD, 0, 0, 0); SBAR(); p[IDX] = __builtin_amdgcn_exp2f(p[IDX]); asm volatile("" : "+v"(p)); SBAR(); } while (0)
; #define SWRITE(so) do { *(bf16x8*)(lds + (so) + vst0) = sr_.vs0; *(bf16x8*)(lds + (so) + vst1) = sr_.vs1;          \
;     *(bf16x8*)(lds + (so) + kst0) = sr_.ks0; *(bf16x8*)(lds + (so) + kst1) = sr_.ks1; } while (0)
; #define SWAIT() asm volatile("s_waitcnt vmcnt(0)" ::: "memory")
; #define RESC(a) do { if (__any((a) < 1.f)) { if (hi == 0) al_l[r32] = (a); asm volatile("s_waitcnt lgkmcnt(0)" ::: "memory"); \
;     _Pragma("unroll") for (int d = 0; d < 4; ++d) _Pragma("unroll") for (int r = 0; r < 16; ++r) o[d][r] *= al_l[crow(r, hi)]; } } while (0)
; #define ROT() do { const int t_ = s_prev; s_prev = s_cur; s_cur = s_next; s_next = t_; } while (0)
; __device__ __forceinline__ void pv_exp(f32x16* o, int vb, bf16x8 pa0, bf16x8 pa1, bf16x8 pa2, bf16x8 pa3, f32x16& p, VF8& fa) {
;   VF8 fb;
;   asm volatile("s_waitcnt lgkmcnt(0)" ::: "memory"); SBAR();
;   PVE_M(o[0], pa0, fa.l0, fa.h0, 0); PVE_M(o[0], pa1, fa.l1, fa.h1, 1); vf8_read<1>(fb, vb); SBAR(); PVE_M(o[0], pa2, fa.l2, fa.h2, 2); PVE_M(o[0], pa3, fa.l3, fa.h3, 3);
;   asm volatile("s_waitcnt lgkmcnt(0)" ::: "memory"); SBAR();
;   PVE_M(o[1], pa0, fb.l0, fb.h0, 4); PVE_M(o[1], pa1, fb.l1, fb.h1, 5); vf8_read<2>(fa, vb); SBAR(); PVE_M(o[1], pa2, fb.l2, fb.h2, 6); PVE_M(o[1], pa3, fb.l3, fb.h3, 7);
;   asm volatile("s_waitcnt lgkmcnt(0)" ::: "memory"); SBAR();
;   PVE_M(o[2], pa0, fa.l0, fa.h0, 8); PVE_M(o[2], pa1, fa.l1, fa.h1, 9); vf8_read<3>(fb, vb); SBAR(); PVE_M(o[2], pa2, fa.l2, fa.h2, 10); PVE_M(o[2], pa3, fa.l3, fa.h3, 11);
;   asm volatile("s_waitcnt lgkmcnt(0)" ::: "memory"); SBAR();
;   PVE_M(o[3], pa0, fb.l0, fb.h0, 12); PVE_M(o[3], pa1, fb.l1, fb.h1, 13); PVE_M(o[3], pa2, fb.l2, fb.h2, 14); PVE_M(o[3], pa3, fb.l3, fb.h3, 15);
; }
; __device__ __forceinline__ void attn_item(const bf16_t* __restrict__ Qb, const bf16_t* __restrict__ Kh, const bf16_t* __restrict__ Vh, const bf16_t* __restrict__ Zb, ...
;     ...
;     partialSM<false, false>(pA0, pA1, m_reg, negm, alA, track); SBAR(); pv_exp(o, vb0 + s_prev, pa0, pa1, pa2, pa3, pA0, vfa);
;     SWAIT(); SWRITE(s_next);
;     RESC(alA); __syncthreads(); ROT();
.LBB0_463:
	s_add_i32 s80, s77, 0
	s_waitcnt lgkmcnt(0)
	v_mfma_f32_32x32x16_bf16 v[50:65], v[132:135], v[144:147], v[50:65]
	v_exp_f32_e32 v114, v114
	v_mfma_f32_32x32x16_bf16 v[50:65], v[136:139], v[106:109], v[50:65]
	v_exp_f32_e32 v115, v115
	ds_read_b64_tr_b16 v[106:107], v203 offset:0x200
	ds_read_b64_tr_b16 v[108:109], v203 offset:0xa00
	ds_read_b64_tr_b16 v[144:145], v203 offset:0x1200
	ds_read_b64_tr_b16 v[146:147], v203 offset:0x1a00
	ds_read_b64_tr_b16 v[204:205], v203 offset:0x2200
	ds_read_b64_tr_b16 v[206:207], v203 offset:0x2a00
	ds_read_b64_tr_b16 v[208:209], v203 offset:0x3200
	ds_read_b64_tr_b16 v[210:211], v203 offset:0x3a00
	s_waitcnt vmcnt(3)
	v_add_u32_e32 v248, s80, v228
	ds_write_b128 v248, v[188:191]
	v_mfma_f32_32x32x16_bf16 v[50:65], v[196:199], v[102:105], v[50:65]
	v_exp_f32_e32 v116, v116
	v_mfma_f32_32x32x16_bf16 v[50:65], v[140:143], v[98:101], v[50:65]
	v_exp_f32_e32 v117, v117
	s_waitcnt lgkmcnt(1)
	v_mfma_f32_32x32x16_bf16 v[34:49], v[132:135], v[106:109], v[34:49]
	v_exp_f32_e32 v118, v118
	v_mfma_f32_32x32x16_bf16 v[34:49], v[136:139], v[144:147], v[34:49]
	v_exp_f32_e32 v119, v119
	ds_read_b64_tr_b16 v[98:99], v203 offset:0x400
	ds_read_b64_tr_b16 v[100:101], v203 offset:0xc00
	ds_read_b64_tr_b16 v[102:103], v203 offset:0x1400
	ds_read_b64_tr_b16 v[104:105], v203 offset:0x1c00
	ds_read_b64_tr_b16 v[106:107], v203 offset:0x2400
	ds_read_b64_tr_b16 v[108:109], v203 offset:0x2c00
	ds_read_b64_tr_b16 v[144:145], v203 offset:0x3400
	ds_read_b64_tr_b16 v[146:147], v203 offset:0x3c00
	s_waitcnt vmcnt(2)
	v_add_u32_e32 v249, s80, v231
	ds_write_b128 v249, v[180:183] offset:16384
	v_mfma_f32_32x32x16_bf16 v[34:49], v[196:199], v[204:207], v[34:49]
	v_exp_f32_e32 v120, v120
	v_mfma_f32_32x32x16_bf16 v[34:49], v[140:143], v[208:211], v[34:49]
	v_exp_f32_e32 v121, v121
	s_waitcnt lgkmcnt(1)
	v_mfma_f32_32x32x16_bf16 v[18:33], v[132:135], v[98:101], v[18:33]
	v_exp_f32_e32 v122, v122
	v_mfma_f32_32x32x16_bf16 v[18:33], v[136:139], v[102:105], v[18:33]
	v_exp_f32_e32 v123, v123
	ds_read_b64_tr_b16 v[98:99], v203 offset:0x600
	ds_read_b64_tr_b16 v[100:101], v203 offset:0xe00
	ds_read_b64_tr_b16 v[102:103], v203 offset:0x1600
	ds_read_b64_tr_b16 v[104:105], v203 offset:0x1e00
	ds_read_b64_tr_b16 v[204:205], v203 offset:0x2600
	ds_read_b64_tr_b16 v[206:207], v203 offset:0x2e00
	ds_read_b64_tr_b16 v[208:209], v203 offset:0x3600
	ds_read_b64_tr_b16 v[210:211], v203 offset:0x3e00
	s_waitcnt vmcnt(1)
	v_add_u32_e32 v250, s80, v229
	ds_write_b128 v250, v[192:195]
	v_mfma_f32_32x32x16_bf16 v[18:33], v[196:199], v[106:109], v[18:33]
	v_exp_f32_e32 v124, v124
	v_mfma_f32_32x32x16_bf16 v[18:33], v[140:143], v[144:147], v[18:33]
	v_exp_f32_e32 v125, v125
	s_waitcnt lgkmcnt(1)
	v_mfma_f32_32x32x16_bf16 v[2:17], v[132:135], v[98:101], v[2:17]
	v_exp_f32_e32 v126, v126
	s_waitcnt vmcnt(0)
	v_add_u32_e32 v251, s80, v232
	ds_write_b128 v251, v[184:187] offset:16384
	v_mfma_f32_32x32x16_bf16 v[2:17], v[136:139], v[102:105], v[2:17]
	v_exp_f32_e32 v127, v127
	v_mfma_f32_32x32x16_bf16 v[2:17], v[196:199], v[204:207], v[2:17]
	v_exp_f32_e32 v128, v128
	v_mfma_f32_32x32x16_bf16 v[2:17], v[140:143], v[208:211], v[2:17]
	v_exp_f32_e32 v129, v129
	v_cmp_gt_f32_e32 vcc, 1.0, v200
	s_cbranch_vccz .LBB0_467
	s_and_saveexec_b64 s[36:37], s[6:7]
	ds_write_b32 v220, v200 offset:128
	s_or_b64 exec, exec, s[36:37]
	s_waitcnt lgkmcnt(0)
	v_add_u32_e32 v110, v213, v212
	ds_read_b128 v[98:101], v110 offset:224
	ds_read_b128 v[102:105], v110 offset:192
	ds_read_b128 v[106:109], v110 offset:160
	ds_read_b128 v[132:135], v110 offset:128
	s_waitcnt lgkmcnt(3)
	v_pk_mul_f32 v[62:63], v[62:63], v[98:99]
	s_waitcnt lgkmcnt(2)
	v_pk_mul_f32 v[58:59], v[58:59], v[102:103]
	s_waitcnt lgkmcnt(1)
	v_pk_mul_f32 v[54:55], v[54:55], v[106:107]
	v_pk_mul_f32 v[64:65], v[64:65], v[100:101]
	v_pk_mul_f32 v[60:61], v[60:61], v[104:105]
	v_pk_mul_f32 v[56:57], v[56:57], v[108:109]
	s_waitcnt lgkmcnt(0)
	v_pk_mul_f32 v[52:53], v[52:53], v[134:135]
	v_pk_mul_f32 v[50:51], v[50:51], v[132:133]
	v_pk_mul_f32 v[46:47], v[46:47], v[98:99]
	v_pk_mul_f32 v[42:43], v[42:43], v[102:103]
	v_pk_mul_f32 v[38:39], v[38:39], v[106:107]
	v_pk_mul_f32 v[48:49], v[48:49], v[100:101]
	v_pk_mul_f32 v[44:45], v[44:45], v[104:105]
	v_pk_mul_f32 v[40:41], v[40:41], v[108:109]
	v_pk_mul_f32 v[36:37], v[36:37], v[134:135]
	v_pk_mul_f32 v[34:35], v[34:35], v[132:133]
	v_pk_mul_f32 v[30:31], v[30:31], v[98:99]
	v_pk_mul_f32 v[26:27], v[26:27], v[102:103]
	v_pk_mul_f32 v[22:23], v[22:23], v[106:107]
	v_pk_mul_f32 v[32:33], v[32:33], v[100:101]
	v_pk_mul_f32 v[28:29], v[28:29], v[104:105]
	v_pk_mul_f32 v[24:25], v[24:25], v[108:109]
	v_pk_mul_f32 v[20:21], v[20:21], v[134:135]
	v_pk_mul_f32 v[18:19], v[18:19], v[132:133]
	v_pk_mul_f32 v[14:15], v[14:15], v[98:99]
	v_pk_mul_f32 v[10:11], v[10:11], v[102:103]
	v_pk_mul_f32 v[6:7], v[6:7], v[106:107]
	v_pk_mul_f32 v[16:17], v[16:17], v[100:101]
	v_pk_mul_f32 v[12:13], v[12:13], v[104:105]
	v_pk_mul_f32 v[8:9], v[8:9], v[108:109]
	v_pk_mul_f32 v[4:5], v[4:5], v[134:135]
	v_pk_mul_f32 v[2:3], v[2:3], v[132:133]

; __global__ void __launch_bounds__(512, 2) fwd_megakernel(Args a) {
	.amdhsa_kernel _Z14fwd_megakernel4Args
		.amdhsa_group_segment_fixed_size 0
		.amdhsa_private_segment_fixed_size 0
		.amdhsa_kernarg_size 352
		.amdhsa_user_sgpr_count 2
		.amdhsa_user_sgpr_dispatch_ptr 0
		.amdhsa_user_sgpr_queue_ptr 0
		.amdhsa_user_sgpr_kernarg_segment_ptr 1
		.amdhsa_user_sgpr_dispatch_id 0
		.amdhsa_user_sgpr_kernarg_preload_length 0
		.amdhsa_user_sgpr_kernarg_preload_offset 0
		.amdhsa_user_sgpr_private_segment_size 0
		.amdhsa_uses_dynamic_stack 0
		.amdhsa_enable_private_segment 0
		.amdhsa_system_sgpr_workgroup_id_x 1
		.amdhsa_system_sgpr_workgroup_id_y 0
		.amdhsa_system_sgpr_workgroup_id_z 0
		.amdhsa_system_sgpr_workgroup_info 0
		.amdhsa_system_vgpr_workitem_id 2
		.amdhsa_next_free_vgpr 256
		.amdhsa_next_free_sgpr 96
		.amdhsa_accum_offset 256
		.amdhsa_reserve_vcc 1
		.amdhsa_float_round_mode_32 0
		.amdhsa_float_round_mode_16_64 0
		.amdhsa_float_denorm_mode_32 3
		.amdhsa_float_denorm_mode_16_64 3
		.amdhsa_dx10_clamp 1
		.amdhsa_ieee_mode 1
		.amdhsa_fp16_overflow 0
		.amdhsa_tg_split 0
		.amdhsa_exception_fp_ieee_invalid_op 0
		.amdhsa_exception_fp_denorm_src 0
		.amdhsa_exception_fp_ieee_div_zero 0
		.amdhsa_exception_fp_ieee_overflow 0
		.amdhsa_exception_fp_ieee_underflow 0
		.amdhsa_exception_fp_ieee_inexact 0
		.amdhsa_exception_int_div_zero 0
	.end_amdhsa_kernel

; __global__ void __launch_bounds__(512, 2) fwd_megakernel(Args a) {
amdhsa.kernels:
  - .agpr_count:     0
    .args:
      - .offset:         0
        .size:           96
        .value_kind:     by_value
      - .offset:         96
        .size:           4
        .value_kind:     hidden_block_count_x
      - .offset:         100
        .size:           4
        .value_kind:     hidden_block_count_y
      - .offset:         104
        .size:           4
        .value_kind:     hidden_block_count_z
      - .offset:         108
        .size:           2
        .value_kind:     hidden_group_size_x
      - .offset:         110
        .size:           2
        .value_kind:     hidden_group_size_y
      - .offset:         112
        .size:           2
        .value_kind:     hidden_group_size_z
      - .offset:         114
        .size:           2
        .value_kind:     hidden_remainder_x
      - .offset:         116
        .size:           2
        .value_kind:     hidden_remainder_y
      - .offset:         118
        .size:           2
        .value_kind:     hidden_remainder_z
      - .offset:         136
        .size:           8
        .value_kind:     hidden_global_offset_x
      - .offset:         144
        .size:           8
        .value_kind:     hidden_global_offset_y
      - .offset:         152
        .size:           8
        .value_kind:     hidden_global_offset_z
      - .offset:         160
        .size:           2
        .value_kind:     hidden_grid_dims
      - .offset:         184
        .size:           8
        .value_kind:     hidden_multigrid_sync_arg
      - .offset:         216
        .size:           4
        .value_kind:     hidden_dynamic_lds_size
    .group_segment_fixed_size: 0
    .kernarg_segment_align: 8
    .kernarg_segment_size: 352
    .language:       OpenCL C
    .language_version:
      - 2
      - 0
    .max_flat_workgroup_size: 512
    .name:           _Z14fwd_megakernel4Args
    .private_segment_fixed_size: 0
    .sgpr_count:     102
    .sgpr_spill_count: 0
    .symbol:         _Z14fwd_megakernel4Args.kd
    .uniform_work_group_size: 1
    .uses_dynamic_stack: false
    .vgpr_count:     256
    .vgpr_spill_count: 0
    .wavefront_size: 64
